# L5b token loop: second 3-load batch issued at the top with the first batch; no wait on the first store before the second compute
# speedup vs baseline: 1.0042x; 1.0042x over previous
.LBB0_1731:
	v_add_co_u32_e32 v16, vcc, 0x1000, v14
	s_nop 1
	s_nop 0
	v_addc_co_u32_e32 v17, vcc, 0, v15, vcc
	s_waitcnt lgkmcnt(0)
	global_load_dwordx4 v[0:3], v[16:17], off offset:1024
	global_load_dwordx4 v[4:7], v[14:15], off
	global_load_dwordx4 v[8:11], v[14:15], off offset:3072
	global_load_dwordx4 v[130:133], v[16:17], off offset:2048
	global_load_dwordx4 v[134:137], v[14:15], off offset:1024
	global_load_dwordx4 v[138:141], v[16:17], off
	s_waitcnt vmcnt(5)
	v_lshlrev_b32_e32 v18, 16, v0
	v_and_b32_e32 v19, 0xffff0000, v0
	s_waitcnt vmcnt(3)
	v_lshlrev_b32_e32 v0, 16, v8
	v_lshlrev_b32_e32 v20, 16, v4
	v_and_b32_e32 v21, 0xffff0000, v4
	v_and_b32_e32 v4, 0xffff0000, v8
	v_mul_f32_e32 v8, 0xbfb8aa3b, v0
	v_exp_f32_e32 v22, v8
	v_mul_f32_e32 v8, 0xbfb8aa3b, v4
	v_exp_f32_e32 v23, v8
	v_pk_add_f32 v[18:19], v[18:19], v[20:21]
	v_pk_add_f32 v[20:21], v[22:23], 1.0 op_sel_hi:[1,0]
	s_nop 0
	s_nop 0
	v_rcp_f32_e32 v8, v21
	s_nop 0
	v_mul_f32_e32 v21, v4, v8
	s_nop 0
	v_rcp_f32_e32 v4, v20
	s_nop 0
	v_mul_f32_e32 v20, v0, v4
	v_pk_mul_f32 v[26:27], v[18:19], v[20:21]
	v_lshlrev_b32_e32 v0, 16, v1
	v_and_b32_e32 v1, 0xffff0000, v1
	v_lshlrev_b32_e32 v4, 16, v5
	v_and_b32_e32 v5, 0xffff0000, v5
	v_lshlrev_b32_e32 v20, 16, v9
	v_and_b32_e32 v21, 0xffff0000, v9
	v_mul_f32_e32 v8, 0xbfb8aa3b, v20
	v_pk_add_f32 v[0:1], v[0:1], v[4:5]
	v_mul_f32_e32 v4, 0xbfb8aa3b, v21
	v_exp_f32_e32 v8, v8
	v_exp_f32_e32 v9, v4
	v_pk_mul_f32 v[18:19], v[26:27], v[26:27]
	v_pk_add_f32 v[4:5], v[8:9], 1.0 op_sel_hi:[1,0]
	s_nop 0
	s_nop 0
	v_rcp_f32_e32 v8, v5
	s_nop 0
	v_mul_f32_e32 v5, v21, v8
	s_nop 0
	v_rcp_f32_e32 v8, v4
	s_nop 0
	v_mul_f32_e32 v4, v20, v8
	v_pk_mul_f32 v[4:5], v[0:1], v[4:5]
	v_lshlrev_b32_e32 v0, 16, v2
	v_and_b32_e32 v1, 0xffff0000, v2
	v_lshlrev_b32_e32 v8, 16, v6
	v_and_b32_e32 v9, 0xffff0000, v6
	v_lshlrev_b32_e32 v2, 16, v10
	v_and_b32_e32 v6, 0xffff0000, v10
	v_mul_f32_e32 v10, 0xbfb8aa3b, v2
	v_pk_add_f32 v[0:1], v[0:1], v[8:9]
	v_mul_f32_e32 v8, 0xbfb8aa3b, v6
	v_exp_f32_e32 v22, v10
	v_exp_f32_e32 v23, v8
	v_pk_mul_f32 v[20:21], v[4:5], v[4:5]
	v_pk_add_f32 v[8:9], v[22:23], 1.0 op_sel_hi:[1,0]
	s_nop 0
	s_nop 0
	v_rcp_f32_e32 v10, v9
	s_nop 0
	v_mul_f32_e32 v9, v6, v10
	s_nop 0
	v_rcp_f32_e32 v6, v8
	s_nop 0
	v_mul_f32_e32 v8, v2, v6
	v_pk_mul_f32 v[8:9], v[0:1], v[8:9]
	v_lshlrev_b32_e32 v0, 16, v3
	v_and_b32_e32 v1, 0xffff0000, v3
	v_lshlrev_b32_e32 v2, 16, v7
	v_and_b32_e32 v3, 0xffff0000, v7
	v_lshlrev_b32_e32 v10, 16, v11
	v_and_b32_e32 v11, 0xffff0000, v11
	v_mul_f32_e32 v6, 0xbfb8aa3b, v10
	v_pk_add_f32 v[0:1], v[0:1], v[2:3]
	v_mul_f32_e32 v2, 0xbfb8aa3b, v11
	v_exp_f32_e32 v6, v6
	v_exp_f32_e32 v7, v2
	v_pk_mul_f32 v[22:23], v[8:9], v[8:9]
	v_pk_add_f32 v[2:3], v[6:7], 1.0 op_sel_hi:[1,0]
	s_nop 0
	s_nop 0
	v_rcp_f32_e32 v6, v3
	s_nop 0
	v_mul_f32_e32 v3, v11, v6
	s_nop 0
	v_rcp_f32_e32 v6, v2
	s_nop 0
	v_mul_f32_e32 v2, v10, v6
	v_pk_mul_f32 v[6:7], v[0:1], v[2:3]
	v_cvt_pk_bf16_f32 v0, v26, v27
	v_cvt_pk_bf16_f32 v1, v4, v5
	v_cvt_pk_bf16_f32 v2, v8, v9
	v_cvt_pk_bf16_f32 v3, v6, v7
	global_store_dwordx4 v[16:17], v[0:3], off offset:1024
	v_pk_mul_f32 v[24:25], v[6:7], v[6:7]
	s_waitcnt vmcnt(3)
	v_lshlrev_b32_e32 v26, 16, v130
	v_and_b32_e32 v27, 0xffff0000, v130
	s_waitcnt vmcnt(1)
	v_lshlrev_b32_e32 v0, 16, v138
	v_lshlrev_b32_e32 v28, 16, v134
	v_and_b32_e32 v29, 0xffff0000, v134
	v_and_b32_e32 v4, 0xffff0000, v138
	v_mul_f32_e32 v8, 0xbfb8aa3b, v0
	v_exp_f32_e32 v38, v8
	v_mul_f32_e32 v8, 0xbfb8aa3b, v4
	v_exp_f32_e32 v39, v8
	v_pk_add_f32 v[26:27], v[26:27], v[28:29]
	v_pk_add_f32 v[28:29], v[38:39], 1.0 op_sel_hi:[1,0]
	s_nop 0
	s_nop 0
	v_rcp_f32_e32 v8, v29
	s_nop 0
	v_mul_f32_e32 v29, v4, v8
	s_nop 0
	v_rcp_f32_e32 v4, v28
	s_nop 0
	v_mul_f32_e32 v28, v0, v4
	v_lshlrev_b32_e32 v0, 16, v131
	v_and_b32_e32 v1, 0xffff0000, v131
	v_lshlrev_b32_e32 v4, 16, v135
	v_and_b32_e32 v5, 0xffff0000, v135
	v_lshlrev_b32_e32 v37, 16, v139
	v_and_b32_e32 v38, 0xffff0000, v139
	v_mul_f32_e32 v8, 0xbfb8aa3b, v37
	v_pk_add_f32 v[0:1], v[0:1], v[4:5]
	v_mul_f32_e32 v4, 0xbfb8aa3b, v38
	v_exp_f32_e32 v8, v8
	v_exp_f32_e32 v9, v4
	v_pk_mul_f32 v[26:27], v[26:27], v[28:29]
	v_pk_add_f32 v[4:5], v[8:9], 1.0 op_sel_hi:[1,0]
	s_nop 0
	v_pk_mul_f32 v[28:29], v[26:27], v[26:27]
	v_rcp_f32_e32 v8, v5
	s_nop 0
	v_mul_f32_e32 v5, v38, v8
	s_nop 0
	v_rcp_f32_e32 v8, v4
	s_nop 0
	v_mul_f32_e32 v4, v37, v8
	v_lshlrev_b32_e32 v8, 16, v132
	v_and_b32_e32 v9, 0xffff0000, v132
	v_lshlrev_b32_e32 v2, 16, v140
	v_lshlrev_b32_e32 v38, 16, v136
	v_and_b32_e32 v39, 0xffff0000, v136
	v_and_b32_e32 v6, 0xffff0000, v140
	v_mul_f32_e32 v10, 0xbfb8aa3b, v2
	v_exp_f32_e32 v40, v10
	v_mul_f32_e32 v10, 0xbfb8aa3b, v6
	v_exp_f32_e32 v41, v10
	v_pk_add_f32 v[8:9], v[8:9], v[38:39]
	v_pk_mul_f32 v[4:5], v[0:1], v[4:5]
	v_pk_add_f32 v[38:39], v[40:41], 1.0 op_sel_hi:[1,0]
	s_nop 0
	v_pk_mul_f32 v[0:1], v[4:5], v[4:5]
	v_rcp_f32_e32 v10, v39
	s_nop 0
	v_mul_f32_e32 v39, v6, v10
	s_nop 0
	v_rcp_f32_e32 v6, v38
	s_nop 0
	v_mul_f32_e32 v38, v2, v6
	v_lshlrev_b32_e32 v2, 16, v133
	v_and_b32_e32 v3, 0xffff0000, v133
	v_lshlrev_b32_e32 v6, 16, v137
	v_and_b32_e32 v7, 0xffff0000, v137
	v_lshlrev_b32_e32 v37, 16, v141
	v_and_b32_e32 v40, 0xffff0000, v141
	v_mul_f32_e32 v10, 0xbfb8aa3b, v37
	v_pk_add_f32 v[2:3], v[2:3], v[6:7]
	v_mul_f32_e32 v6, 0xbfb8aa3b, v40
	v_exp_f32_e32 v10, v10
	v_exp_f32_e32 v11, v6
	v_pk_mul_f32 v[8:9], v[8:9], v[38:39]
	v_pk_add_f32 v[6:7], v[10:11], 1.0 op_sel_hi:[1,0]
	s_nop 0
	v_pk_mul_f32 v[38:39], v[8:9], v[8:9]
	v_rcp_f32_e32 v10, v7
	s_nop 0
	v_mul_f32_e32 v7, v40, v10
	s_nop 0
	v_rcp_f32_e32 v10, v6
	s_nop 0
	v_mul_f32_e32 v6, v37, v10
	v_add_f32_e32 v10, v18, v19
	v_add_f32_e32 v10, v20, v10
	v_add_f32_e32 v10, v21, v10
	v_add_f32_e32 v10, v22, v10
	v_add_f32_e32 v10, v23, v10
	v_add_f32_e32 v10, v24, v10
	v_add_f32_e32 v10, v25, v10
	v_add_f32_e32 v10, v28, v10
	v_add_f32_e32 v10, v29, v10
	v_add_f32_e32 v0, v0, v10
	v_add_f32_e32 v0, v1, v0
	v_pk_mul_f32 v[6:7], v[2:3], v[6:7]
	v_add_f32_e32 v0, v38, v0
	v_pk_mul_f32 v[2:3], v[6:7], v[6:7]
	v_add_f32_e32 v0, v39, v0
	v_add_f32_e32 v0, v2, v0
	v_add_f32_e32 v10, v3, v0
	v_cvt_pk_bf16_f32 v0, v26, v27
	v_cvt_pk_bf16_f32 v1, v4, v5
	v_cvt_pk_bf16_f32 v2, v8, v9
	v_cvt_pk_bf16_f32 v3, v6, v7
	global_store_dwordx4 v[16:17], v[0:3], off offset:2048
	ds_bpermute_b32 v0, v31, v10
	s_waitcnt lgkmcnt(0)
	v_add_f32_e32 v0, v10, v0
	ds_bpermute_b32 v1, v32, v0
	s_waitcnt lgkmcnt(0)
	v_add_f32_e32 v0, v0, v1
	ds_bpermute_b32 v1, v33, v0
	s_waitcnt lgkmcnt(0)
	v_add_f32_e32 v0, v0, v1
	ds_bpermute_b32 v1, v34, v0
	s_waitcnt lgkmcnt(0)
	v_add_f32_e32 v0, v0, v1
	ds_bpermute_b32 v1, v35, v0
	s_waitcnt lgkmcnt(0)
	v_add_f32_e32 v0, v0, v1
	ds_bpermute_b32 v1, v36, v0
	s_and_saveexec_b64 s[10:11], s[4:5]
	s_cbranch_execz .LBB0_1730
	s_waitcnt lgkmcnt(0)
	v_add_f32_e32 v0, v0, v1
	v_fmamk_f32 v0, v0, 0x3a800000, v206
	v_mul_f32_e32 v1, 0x4b800000, v0
	v_cmp_gt_f32_e32 vcc, s83, v0
	s_nop 1
	s_nop 0
	v_cndmask_b32_e32 v0, v0, v1, vcc
	v_rsq_f32_e32 v0, v0
	s_nop 0
	v_mul_f32_e32 v1, 0x45800000, v0
	v_cndmask_b32_e32 v0, v0, v1, vcc
	global_store_dword v[12:13], v0, off
	s_branch .LBB0_1730
